# v23 + nt on the P4a RP / Y0 stores (consumed only in P4c)
# baseline (speedup 1.0000x reference)
; __device__ __forceinline__ unsigned pk2(float lo, float hi) { f32x2_t v = {lo, hi}; bf16x2_t b = __builtin_convertvector(v, bf16x2_t); return __builtin_bit_cast(unsigned, b); }
; #define LBAR() do { asm volatile("s_waitcnt lgkmcnt(0)" ::: "memory"); __builtin_amdgcn_s_barrier(); asm volatile("" ::: "memory"); } while (0)
; __device__ __forceinline__ f32x4 bf4(u32x2 w) { return (f32x4){__uint_as_float(w.x << 16), __uint_as_float(w.x & 0xffff0000u), __uint_as_float(w.y << 16), __uint_as_float(w.y & 0xffff0000u)}; }
; __device__ __forceinline__ void chunk_item(const PAArgs& A, unsigned char* lds, int item, int tid, int wave, int lane, const ChunkRaw& RAW) {
;     ...
;     {
;         typedef short s16x4 __attribute__((ext_vector_type(4)));
;         const int cb = (wave & 3) * 16 + fr;
;         const bf16* src = (wave < 4 ? ATT : AVT) + cb * MST;
;         bf16* dst = (wave < 4 ? X1T : ZT) + cb * MST;
;         s16x4 xb[4];
; #pragma unroll
;         for (int bi = 0; bi < 4; ++bi) {
;             f32x4 acc = bf4(*(const u32x2*)(src + bi * 16 + fq * 4));
; #pragma unroll
;             for (int bj = 0; bj < bi; ++bj) acc = __builtin_amdgcn_mfma_f32_16x16x16bf16_1k(*(const s16x4*)(AABb + (bi * 16 + fr) * MST + bj * 16 + fq * 4), xb[bj], acc, 0, 0, 0);
;             const u32x2 tb = (u32x2){pk2(acc[0], acc[1]), pk2(acc[2], acc[3])};
;             const f32x4 xv = __builtin_amdgcn_mfma_f32_16x16x16bf16_1k(*(const s16x4*)(Tinv + (bi * 16 + fr) * TST + fq * 4), __builtin_bit_cast(s16x4, tb), z4, 0, 0, 0);
;             const u32x2 xw = (u32x2){pk2(xv[0], xv[1]), pk2(xv[2], xv[3])};
;             xb[bi] = __builtin_bit_cast(s16x4, xw);
;             *(u32x2*)(dst + bi * 16 + fq * 4) = xw;
;         }
;     }
;     LBAR();
.LBB0_428:
	s_waitcnt lgkmcnt(0)
	s_barrier
	ds_read_b64 v[0:1], v75
	v_add_u32_e32 v18, 0x800, v98
	s_mov_b32 s6, 0x6000000
	s_waitcnt lgkmcnt(0)
	v_lshlrev_b32_e32 v2, 16, v0
	v_and_b32_e32 v0, 0xffff0000, v0
	v_lshlrev_b32_e32 v3, 16, v1
	v_and_b32_e32 v1, 0xffff0000, v1
	v_cvt_pk_bf16_f32 v0, v2, v0
	v_cvt_pk_bf16_f32 v1, v3, v1
	ds_read_b64 v[2:3], v97
	s_waitcnt lgkmcnt(0)
	v_mfma_f32_16x16x16_bf16 v[0:3], v[2:3], v[0:1], 0
	s_nop 7
	v_cvt_pk_bf16_f32 v0, v0, v1
	v_cvt_pk_bf16_f32 v1, v2, v3
	ds_write_b64 v76, v[0:1]
	ds_read_b64 v[6:7], v98
	ds_read_b64 v[4:5], v75 offset:32
	s_waitcnt lgkmcnt(0)
	v_lshlrev_b32_e32 v2, 16, v4
	v_and_b32_e32 v3, 0xffff0000, v4
	v_lshlrev_b32_e32 v4, 16, v5
	v_and_b32_e32 v5, 0xffff0000, v5
	s_nop 1
	v_mfma_f32_16x16x16_bf16 v[2:5], v[6:7], v[0:1], v[2:5]
	s_nop 7
	v_cvt_pk_bf16_f32 v2, v2, v3
	v_cvt_pk_bf16_f32 v3, v4, v5
	ds_read_b64 v[4:5], v97 offset:640
	s_waitcnt lgkmcnt(0)
	v_mfma_f32_16x16x16_bf16 v[2:5], v[4:5], v[2:3], 0
	s_nop 7
	v_cvt_pk_bf16_f32 v6, v2, v3
	v_cvt_pk_bf16_f32 v7, v4, v5
	ds_write_b64 v76, v[6:7] offset:32
	ds_read2_b64 v[18:21], v18 offset0:32 offset1:36
	ds_read_b64 v[4:5], v75 offset:64
	s_waitcnt lgkmcnt(0)
	v_lshlrev_b32_e32 v2, 16, v4
	v_and_b32_e32 v3, 0xffff0000, v4
	v_lshlrev_b32_e32 v4, 16, v5
	v_and_b32_e32 v5, 0xffff0000, v5
	s_nop 1
	v_mfma_f32_16x16x16_bf16 v[2:5], v[18:19], v[0:1], v[2:5]
	v_add_u32_e32 v18, 0x1000, v98
	v_mfma_f32_16x16x16_bf16 v[2:5], v[20:21], v[6:7], v[2:5]
	s_nop 7
	v_cvt_pk_bf16_f32 v2, v2, v3
	v_cvt_pk_bf16_f32 v3, v4, v5
	ds_read_b64 v[4:5], v97 offset:1280
	s_waitcnt lgkmcnt(0)
	v_mfma_f32_16x16x16_bf16 v[2:5], v[4:5], v[2:3], 0
	s_nop 7
	v_cvt_pk_bf16_f32 v116, v2, v3
	v_cvt_pk_bf16_f32 v117, v4, v5
	ds_write_b64 v76, v[116:117] offset:64
	ds_read2_b64 v[18:21], v18 offset0:64 offset1:68
	ds_read_b64 v[4:5], v75 offset:96
	s_waitcnt lgkmcnt(0)
	v_lshlrev_b32_e32 v2, 16, v4
	v_and_b32_e32 v3, 0xffff0000, v4
	v_lshlrev_b32_e32 v4, 16, v5
	v_and_b32_e32 v5, 0xffff0000, v5
	s_nop 1
	v_mfma_f32_16x16x16_bf16 v[0:3], v[18:19], v[0:1], v[2:5]
	s_nop 2
	ds_read_b64 v[4:5], v98 offset:4672
	v_mfma_f32_16x16x16_bf16 v[0:3], v[20:21], v[6:7], v[0:3]
	s_waitcnt lgkmcnt(0)
	v_mfma_f32_16x16x16_bf16 v[0:3], v[4:5], v[116:117], v[0:3]
	s_nop 7
	v_cvt_pk_bf16_f32 v0, v0, v1
	v_cvt_pk_bf16_f32 v1, v2, v3
	ds_read_b64 v[2:3], v97 offset:1920
	s_waitcnt lgkmcnt(0)
	v_mfma_f32_16x16x16_bf16 v[0:3], v[2:3], v[0:1], 0
	s_nop 7
	v_cvt_pk_bf16_f32 v0, v0, v1
	v_cvt_pk_bf16_f32 v1, v2, v3
	ds_write_b64 v76, v[0:1] offset:96
	s_waitcnt lgkmcnt(0)
	s_barrier
; __device__ __forceinline__ unsigned pk2(float lo, float hi) { f32x2_t v = {lo, hi}; bf16x2_t b = __builtin_convertvector(v, bf16x2_t); return __builtin_bit_cast(unsigned, b); }
; __device__ __forceinline__ void chunk_item(const PAArgs& A, unsigned char* lds, int item, int tid, int wave, int lane, const ChunkRaw& RAW) {
;     ...
;     {
;         f32x4 c0, c1;
;         const int fl = lane * 4;
;         { const u32x2 w0 = *(const u32x2*)(RT + (tj0 * 16 + fr) * MST + ti * 16 + fq * 4), w1 = *(const u32x2*)(RT + (tj0 * 16 + 16 + fr) * MST + ti * 16 + fq * 4);
;           c0 = (f32x4){__uint_as_float(w0.x << 16), __uint_as_float(w0.x & 0xffff0000u), __uint_as_float(w0.y << 16), __uint_as_float(w0.y & 0xffff0000u)};
;           c1 = (f32x4){__uint_as_float(w1.x << 16), __uint_as_float(w1.x & 0xffff0000u), __uint_as_float(w1.y << 16), __uint_as_float(w1.y & 0xffff0000u)}; }
;         mm2(X1T, ARB, ti, tj0, fr, fq, c0, c1);
;         const int fpos = (((ti >> 1) * 64) + ((ti & 1) * 2 + (fq >> 1)) * 16 + fr) * 8 + (fq & 1) * 4;
;         *(u32x2*)(RPg + tj0 * 1024 + fpos) = (u32x2){pk2(c0[0], c0[1]), pk2(c0[2], c0[3])};
;         *(u32x2*)(RPg + (tj0 + 1) * 1024 + fpos) = (u32x2){pk2(c1[0], c1[1]), pk2(c1[2], c1[3])};
;         c0 = z4; c1 = z4; mm2(ZT, ARB, ti, tj0, fr, fq, c0, c1); mm2(VT, ARK, ti, tj0, fr, fq, c0, c1);
;         *(u32x2*)(Y0g + (ti * 4 + tj0) * 256 + fl) = (u32x2){pk2(c0[0], c0[1]), pk2(c0[2], c0[3])};
;         *(u32x2*)(Y0g + (ti * 4 + tj0 + 1) * 256 + fl) = (u32x2){pk2(c1[0], c1[1]), pk2(c1[2], c1[3])};
;         c0 = z4; c1 = z4; mm2(X1T, BHT, ti, tj0, fr, fq, c0, c1);
;         { const int chp = ti * 16 + fq * 4, cha = tj0 * 16 + fr, chb = cha + 16; const float wa = WCs[cha], wb = WCs[chb];
; #pragma unroll
;           for (int r = 0; r < 4; ++r) { c0[r] += (chp + r == cha) ? wa : 0.f; c1[r] += (chp + r == chb) ? wb : 0.f; }
;           *(u32x2*)(Pg + tj0 * 1024 + fpos) = (u32x2){pk2(c0[0], c0[1]), pk2(c0[2], c0[3])};
;           *(u32x2*)(Pg + (tj0 + 1) * 1024 + fpos) = (u32x2){pk2(c1[0], c1[1]), pk2(c1[2], c1[3])}; }
;         c0 = z4; c1 = z4; mm2(BHT, ZT, ti, tj0, fr, fq, c0, c1); mm2(KHT, VT, ti, tj0, fr, fq, c0, c1);
;         *(f32x4*)(Qg + (ti * 4 + tj0) * 256 + fl) = c0;
;         *(f32x4*)(Qg + (ti * 4 + tj0 + 1) * 256 + fl) = c1;
;     }
	ds_read_b64 v[2:3], v79 offset:27648
	ds_read_b64 v[4:5], v79 offset:29952
	s_waitcnt lgkmcnt(1)
	v_lshlrev_b32_e32 v0, 16, v2
	s_waitcnt lgkmcnt(0)
	v_lshlrev_b32_e32 v18, 16, v4
	v_and_b32_e32 v19, 0xffff0000, v4
	v_lshlrev_b32_e32 v20, 16, v5
	v_and_b32_e32 v21, 0xffff0000, v5
	ds_read_b128 v[4:7], v80
	ds_read_b128 v[116:119], v88
	ds_read_b128 v[120:123], v89
	v_and_b32_e32 v1, 0xffff0000, v2
	v_lshlrev_b32_e32 v2, 16, v3
	v_and_b32_e32 v3, 0xffff0000, v3
	s_waitcnt lgkmcnt(0)
	v_mfma_f32_16x16x32_bf16 v[18:21], v[4:7], v[120:123], v[18:21]
	v_mfma_f32_16x16x32_bf16 v[124:127], v[4:7], v[116:119], v[0:3]
	s_nop 2
	ds_read_b128 v[0:3], v80 offset:64
	ds_read_b128 v[128:131], v88 offset:64
	ds_read_b128 v[132:135], v89 offset:64
	s_waitcnt lgkmcnt(1)
	v_mfma_f32_16x16x32_bf16 v[124:127], v[0:3], v[128:131], v[124:127]
	s_waitcnt lgkmcnt(0)
	v_mfma_f32_16x16x32_bf16 v[18:21], v[0:3], v[132:135], v[18:21]
	s_nop 5
	v_cvt_pk_bf16_f32 v124, v124, v125
	v_cvt_pk_bf16_f32 v125, v126, v127
	v_lshl_add_u64 v[126:127], v[16:17], 0, s[50:51]
	v_add_co_u32_e32 v126, vcc, s6, v126
	s_brev_b32 s6, 32
	s_nop 0
	v_addc_co_u32_e32 v127, vcc, 0, v127, vcc
	v_cvt_pk_bf16_f32 v18, v18, v19
	v_cvt_pk_bf16_f32 v19, v20, v21
	global_store_dwordx2 v[126:127], v[18:19], off offset:2048 nt
	ds_read_b128 v[18:21], v90
	s_waitcnt lgkmcnt(0)
	v_mfma_f32_16x16x32_bf16 v[116:119], v[18:21], v[116:119], 0
	global_store_dwordx2 v[126:127], v[124:125], off nt
	v_lshl_add_u64 v[16:17], v[16:17], 0, s[52:53]
	v_mfma_f32_16x16x32_bf16 v[18:21], v[18:21], v[120:123], 0
	ds_read_b128 v[120:123], v90 offset:64
	s_waitcnt lgkmcnt(0)
	v_mfma_f32_16x16x32_bf16 v[116:119], v[120:123], v[128:131], v[116:119]
	v_mfma_f32_16x16x32_bf16 v[18:21], v[120:123], v[132:135], v[18:21]
	ds_read_b128 v[120:123], v52 offset:55296
	ds_read_b128 v[124:127], v91
	ds_read_b128 v[128:131], v92
	s_waitcnt lgkmcnt(1)
	v_mfma_f32_16x16x32_bf16 v[116:119], v[120:123], v[124:127], v[116:119]
	s_waitcnt lgkmcnt(0)
	v_mfma_f32_16x16x32_bf16 v[18:21], v[120:123], v[128:131], v[18:21]
	ds_read_b128 v[120:123], v52 offset:55360
	ds_read_b128 v[124:127], v91 offset:64
	ds_read_b128 v[128:131], v92 offset:64
	s_waitcnt lgkmcnt(1)
	v_mfma_f32_16x16x32_bf16 v[116:119], v[120:123], v[124:127], v[116:119]
	v_perm_b32 v126, v106, v104, s37
	v_perm_b32 v127, v105, v103, s37
	s_waitcnt lgkmcnt(0)
	v_mfma_f32_16x16x32_bf16 v[18:21], v[120:123], v[128:131], v[18:21]
	s_nop 3
	v_cvt_pk_bf16_f32 v116, v116, v117
	v_cvt_pk_bf16_f32 v117, v118, v119
	v_lshl_add_u64 v[118:119], v[14:15], 0, s[50:51]
	v_add_co_u32_e32 v118, vcc, s6, v118
	s_mov_b32 s6, 0x1b800000
	s_nop 0
	v_addc_co_u32_e32 v119, vcc, 0, v119, vcc
	v_cvt_pk_bf16_f32 v18, v18, v19
	v_cvt_pk_bf16_f32 v19, v20, v21
	global_store_dwordx2 v[118:119], v[116:117], off nt
	global_store_dwordx2 v[118:119], v[18:19], off offset:512 nt
	ds_read_b128 v[18:21], v53 offset:36864
	ds_read_b128 v[116:119], v53 offset:39168
	s_waitcnt lgkmcnt(1)
	v_mfma_f32_16x16x32_bf16 v[18:21], v[4:7], v[18:21], 0
	v_lshl_add_u64 v[14:15], v[14:15], 0, s[52:53]
	s_waitcnt lgkmcnt(0)
	v_mfma_f32_16x16x32_bf16 v[4:7], v[4:7], v[116:119], 0
	ds_read_b128 v[116:119], v53 offset:36928
	ds_read_b128 v[120:123], v53 offset:39232
	s_waitcnt lgkmcnt(1)
	v_mfma_f32_16x16x32_bf16 v[18:21], v[0:3], v[116:119], v[18:21]
	s_waitcnt lgkmcnt(0)
	v_mfma_f32_16x16x32_bf16 v[0:3], v[0:3], v[120:123], v[4:7]
	s_nop 2
	ds_read_b32 v6, v81
	ds_read_b32 v115, v82
	s_waitcnt lgkmcnt(1)
	v_cndmask_b32_e64 v4, 0, v6, s[84:85]
	v_add_f32_e32 v18, v18, v4
	v_cndmask_b32_e64 v4, 0, v6, s[86:87]
	v_add_f32_e32 v19, v19, v4
	s_waitcnt lgkmcnt(0)
	v_cndmask_b32_e64 v5, 0, v115, s[90:91]
	v_cndmask_b32_e64 v4, 0, v115, s[88:89]
	v_pk_add_f32 v[0:1], v[0:1], v[4:5]
	v_cndmask_b32_e64 v5, 0, v6, s[92:93]
	v_cndmask_b32_e64 v4, 0, v6, s[94:95]
	v_pk_add_f32 v[4:5], v[20:21], v[4:5]
	v_cndmask_b32_e64 v7, 0, v115, s[96:97]
	v_cndmask_b32_e64 v6, 0, v115, s[18:19]
	v_pk_add_f32 v[2:3], v[2:3], v[6:7]
	v_cvt_pk_bf16_f32 v7, v4, v5
	v_lshl_add_u64 v[4:5], v[12:13], 0, s[50:51]
	v_add_co_u32_e32 v4, vcc, s6, v4
	v_cvt_pk_bf16_f32 v6, v18, v19
	s_nop 0
	v_addc_co_u32_e32 v5, vcc, 0, v5, vcc
	v_cvt_pk_bf16_f32 v0, v0, v1
	v_cvt_pk_bf16_f32 v1, v2, v3
	global_store_dwordx2 v[4:5], v[6:7], off
	global_store_dwordx2 v[4:5], v[0:1], off offset:2048
	ds_read_b128 v[0:3], v52 offset:36864
	ds_read_b128 v[4:7], v93
	ds_read_b128 v[18:21], v94
	s_waitcnt lgkmcnt(1)
	v_mfma_f32_16x16x32_bf16 v[4:7], v[0:3], v[4:7], 0
	v_lshl_add_u64 v[12:13], v[12:13], 0, s[52:53]
	s_and_b64 vcc, exec, s[40:41]
	s_waitcnt lgkmcnt(0)
	v_mfma_f32_16x16x32_bf16 v[0:3], v[0:3], v[18:21], 0
	ds_read_b128 v[18:21], v52 offset:36928
	ds_read_b128 v[116:119], v93 offset:64
	ds_read_b128 v[120:123], v94 offset:64
	s_waitcnt lgkmcnt(1)
	v_mfma_f32_16x16x32_bf16 v[4:7], v[18:21], v[116:119], v[4:7]
	s_waitcnt lgkmcnt(0)
	v_mfma_f32_16x16x32_bf16 v[0:3], v[18:21], v[120:123], v[0:3]
	ds_read_b128 v[18:21], v52 offset:46080
	ds_read_b128 v[116:119], v53 offset:55296
	ds_read_b128 v[120:123], v53 offset:57600
	s_waitcnt lgkmcnt(1)
	v_mfma_f32_16x16x32_bf16 v[4:7], v[18:21], v[116:119], v[4:7]
	s_waitcnt lgkmcnt(0)
	v_mfma_f32_16x16x32_bf16 v[0:3], v[18:21], v[120:123], v[0:3]
	ds_read_b128 v[18:21], v52 offset:46144
	ds_read_b128 v[116:119], v53 offset:55360
	ds_read_b128 v[120:123], v53 offset:57664
	s_waitcnt lgkmcnt(1)
	v_mfma_f32_16x16x32_bf16 v[4:7], v[18:21], v[116:119], v[4:7]
	s_waitcnt lgkmcnt(0)
	v_mfma_f32_16x16x32_bf16 v[0:3], v[18:21], v[120:123], v[0:3]
	s_nop 5
	global_store_dwordx4 v[10:11], v[4:7], off offset:-1024
	s_nop 0
	global_store_dwordx4 v[10:11], v[0:3], off
	s_nop 1
	v_perm_b32 v3, v114, v112, s37
	v_perm_b32 v5, v113, v111, s37
	v_perm_b32 v122, v110, v108, s37
	v_perm_b32 v123, v109, v107, s37
	v_perm_b32 v6, v102, v100, s37
	v_perm_b32 v7, v101, v99, s37
	v_lshl_add_u64 v[10:11], v[10:11], 0, s[24:25]
	s_cbranch_vccnz .LBB0_437
